# attention loop: scalar-base K/V prefetch addresses, bias column offsets folded (two VALU ops fewer per element), QK key-fragment LDS reads hoisted above the prefetch block; on top of the TOP-polling b
# speedup vs baseline: 1.0043x; 1.0043x over previous
.LBB0_393:
	v_mov_b32_e32 v33, v131
	s_add_i32 s64, s65, 1
	v_lshlrev_b32_e32 v34, 4, v33
	v_and_b32_e32 v32, 0x70, v34
	v_add_u32_e32 v32, v143, v32
	v_and_b32_e32 v34, 48, v34
	v_lshrrev_b32_e32 v35, 3, v33
	v_add_u32_e32 v34, v143, v34
	v_mad_u64_u32 v[36:37], s[8:9], v35, s48, v[32:33]
	v_lshrrev_b32_e32 v35, 2, v33
	s_waitcnt vmcnt(7)
	ds_write_b128 v36, v[80:83]
	v_mad_u64_u32 v[36:37], s[8:9], v35, s61, v[34:35]
	v_add_u32_e32 v35, 64, v33
	s_waitcnt vmcnt(6)
	ds_write_b128 v36, v[84:87] offset:4608
	v_lshrrev_b32_e32 v36, 3, v35
	v_mad_u64_u32 v[36:37], s[8:9], v36, s48, v[32:33]
	v_lshrrev_b32_e32 v35, 2, v35
	s_waitcnt vmcnt(5)
	ds_write_b128 v36, v[88:91]
	v_mad_u64_u32 v[36:37], s[8:9], v35, s61, v[34:35]
	v_add_u32_e32 v35, 0x80, v33
	s_waitcnt vmcnt(4)
	ds_write_b128 v36, v[92:95] offset:4608
	v_lshrrev_b32_e32 v36, 3, v35
	v_mad_u64_u32 v[36:37], s[8:9], v36, s48, v[32:33]
	v_lshrrev_b32_e32 v35, 2, v35
	s_waitcnt vmcnt(3)
	ds_write_b128 v36, v[96:99]
	v_mad_u64_u32 v[36:37], s[8:9], v35, s61, v[34:35]
	v_add_u32_e32 v35, 0xc0, v33
	v_lshrrev_b32_e32 v33, 3, v35
	v_mad_u64_u32 v[32:33], s[8:9], v33, s48, v[32:33]
	s_waitcnt vmcnt(2)
	ds_write_b128 v36, v[100:103] offset:4608
	s_waitcnt vmcnt(1)
	ds_write_b128 v32, v[104:107]
	v_lshrrev_b32_e32 v32, 2, v35
	v_mad_u64_u32 v[32:33], s[8:9], v32, s61, v[34:35]
	v_cmp_lt_u32_e32 vcc, s64, v150
	s_waitcnt vmcnt(0)
	ds_write_b128 v32, v[108:111] offset:4608
	ds_read_b128 v[158:161], v147
	ds_read_b128 v[162:165], v147 offset:32
	ds_read_b128 v[166:169], v147 offset:64
	ds_read_b128 v[170:173], v147 offset:96
	s_and_saveexec_b64 s[8:9], vcc
	s_cbranch_execz .LBB0_401
	v_mov_b32_e32 v38, v131
	v_mov_b64_e32 v[32:33], 0x100
	v_mov_b32_e32 v112, s63
	v_mov_b64_e32 v[36:37], v[128:129]
	v_mov_b64_e32 v[34:35], v[138:139]
	s_and_saveexec_b64 s[44:45], s[6:7]
	s_cbranch_execz .LBB0_400
	s_cmp_gt_u32 s65, 14
	s_mov_b64 s[46:47], -1
	s_cbranch_scc0 .LBB0_397
	s_add_i32 s36, s65, -15
	s_lshr_b32 s36, s36, 1
	v_add_u32_e32 v36, s36, v119
	s_and_b32 s66, s63, 32
	v_lshl_or_b32 v112, v36, 6, s66
	v_lshlrev_b64 v[32:33], 10, v[112:113]
	v_lshlrev_b32_e32 v112, 7, v36
	v_lshl_add_u64 v[34:35], v[134:135], 0, v[32:33]
	v_lshl_add_u64 v[36:37], v[136:137], 0, v[112:113]
	s_mov_b64 s[46:47], 0

.LBB0_400:
	s_or_b64 exec, exec, s[44:45]
	v_lshl_add_u64 v[36:37], v[112:113], 1, v[36:37]
	v_readfirstlane_b32 s68, v34
	v_readfirstlane_b32 s69, v35
	v_readfirstlane_b32 s72, v32
	v_and_b32_e32 v213, 7, v38
	v_lshrrev_b32_e32 v214, 3, v38
	v_readfirstlane_b32 s70, v36
	v_readfirstlane_b32 s71, v37
	v_lshlrev_b32_e32 v213, 4, v213
	v_and_b32_e32 v215, 3, v38
	v_lshl_add_u32 v213, v214, 10, v213
	v_lshrrev_b32_e32 v216, 2, v38
	s_lshl_b32 s72, s72, 1
	v_lshlrev_b32_e32 v215, 4, v215
	s_lshl_b32 s73, s72, 4
	v_mad_u32_u24 v216, v216, s72, v215
	s_add_u32 s80, s68, 0x2000
	s_addc_u32 s81, s69, 0
	s_add_u32 s82, s68, 0x4000
	s_addc_u32 s83, s69, 0
	s_add_u32 s84, s68, 0x6000
	s_addc_u32 s85, s69, 0
	s_add_u32 s74, s70, s73
	s_addc_u32 s75, s71, 0
	s_add_u32 s76, s74, s73
	s_addc_u32 s77, s75, 0
	s_add_u32 s78, s76, s73
	s_addc_u32 s79, s77, 0
	global_load_dwordx4 v[80:83], v213, s[68:69]
	global_load_dwordx4 v[84:87], v216, s[70:71]
	global_load_dwordx4 v[88:91], v213, s[80:81]
	global_load_dwordx4 v[92:95], v216, s[74:75]
	global_load_dwordx4 v[96:99], v213, s[82:83]
	global_load_dwordx4 v[100:103], v216, s[76:77]
	global_load_dwordx4 v[104:107], v213, s[84:85]
	global_load_dwordx4 v[108:111], v216, s[78:79]
.LBB0_401:
	s_or_b64 exec, exec, s[8:9]
	s_cmp_gt_u32 s65, 15
	s_cselect_b64 s[8:9], -1, 0
	s_and_b64 s[8:9], s[42:43], s[8:9]
	s_waitcnt lgkmcnt(3)
	v_mfma_f32_32x32x16_bf16 v[32:47], v[158:161], v[64:67], 0
	s_waitcnt lgkmcnt(2)
	v_mfma_f32_32x32x16_bf16 v[32:47], v[162:165], v[68:71], v[32:47]
	s_waitcnt lgkmcnt(1)
	v_mfma_f32_32x32x16_bf16 v[32:47], v[166:169], v[72:75], v[32:47]
	s_waitcnt lgkmcnt(0)
	v_mfma_f32_32x32x16_bf16 v[32:47], v[170:173], v[76:79], v[32:47]
	s_and_saveexec_b64 s[44:45], s[8:9]
	s_cbranch_execz .LBB0_392
	s_add_i32 s9, s65, -16
	s_ashr_i32 s9, s9, 1
	s_sub_i32 s8, s63, 32
	v_add_u32_e32 v48, s9, v152
	v_and_or_b32 v112, s8, 32, v145
	v_mad_u64_u32 v[140:141], s[8:9], v48, 31, v[120:121]
	v_subrev_u32_e32 v207, s14, v132
	v_add_u32_e32 v140, 15, v140
	v_mov_b32_e32 v210, 0xf149f2ca
	v_lshl_add_u32 v207, v140, 2, v207
	v_sub_u32_e32 v188, v112, v151
	v_sub_u32_e32 v189, v112, v153
	v_add_u32_e32 v209, 0, v188
	v_med3_i32 v209, v209, -15, 15
	v_lshl_add_u32 v209, v209, 2, v207
	global_load_dword v190, v209, s[14:15]
	v_add_u32_e32 v209, 1, v188
	v_med3_i32 v209, v209, -15, 15
	v_lshl_add_u32 v209, v209, 2, v207
	global_load_dword v191, v209, s[14:15]
	v_add_u32_e32 v209, 2, v188
	v_med3_i32 v209, v209, -15, 15
	v_lshl_add_u32 v209, v209, 2, v207
	global_load_dword v192, v209, s[14:15]
	v_add_u32_e32 v209, 3, v188
	v_med3_i32 v209, v209, -15, 15
	v_lshl_add_u32 v209, v209, 2, v207
	global_load_dword v193, v209, s[14:15]
	v_add_u32_e32 v209, 8, v188
	v_med3_i32 v209, v209, -15, 15
	v_lshl_add_u32 v209, v209, 2, v207
	global_load_dword v194, v209, s[14:15]
	v_add_u32_e32 v209, 9, v188
	v_med3_i32 v209, v209, -15, 15
	v_lshl_add_u32 v209, v209, 2, v207
	global_load_dword v195, v209, s[14:15]
	v_add_u32_e32 v209, 10, v188
	v_med3_i32 v209, v209, -15, 15
	v_lshl_add_u32 v209, v209, 2, v207
	global_load_dword v196, v209, s[14:15]
	v_add_u32_e32 v209, 11, v188
	v_med3_i32 v209, v209, -15, 15
	v_lshl_add_u32 v209, v209, 2, v207
	global_load_dword v197, v209, s[14:15]
	v_add_u32_e32 v209, 16, v188
	v_med3_i32 v209, v209, -15, 15
	v_lshl_add_u32 v209, v209, 2, v207
	global_load_dword v198, v209, s[14:15]
	v_add_u32_e32 v209, 17, v188
	v_med3_i32 v209, v209, -15, 15
	v_lshl_add_u32 v209, v209, 2, v207
	global_load_dword v199, v209, s[14:15]
	v_add_u32_e32 v209, 18, v188
	v_med3_i32 v209, v209, -15, 15
	v_lshl_add_u32 v209, v209, 2, v207
	global_load_dword v200, v209, s[14:15]
	v_add_u32_e32 v209, 19, v188
	v_med3_i32 v209, v209, -15, 15
	v_lshl_add_u32 v209, v209, 2, v207
	global_load_dword v201, v209, s[14:15]
	v_add_u32_e32 v209, 24, v188
	v_med3_i32 v209, v209, -15, 15
	v_lshl_add_u32 v209, v209, 2, v207
	global_load_dword v202, v209, s[14:15]
	v_add_u32_e32 v209, 25, v188
	v_med3_i32 v209, v209, -15, 15
	v_lshl_add_u32 v209, v209, 2, v207
	global_load_dword v203, v209, s[14:15]
	v_add_u32_e32 v209, 26, v188
	v_med3_i32 v209, v209, -15, 15
	v_lshl_add_u32 v209, v209, 2, v207
	global_load_dword v204, v209, s[14:15]
	v_add_u32_e32 v209, 27, v188
	v_med3_i32 v209, v209, -15, 15
	v_lshl_add_u32 v209, v209, 2, v207
	global_load_dword v205, v209, s[14:15]
	v_add_u32_e32 v208, 0, v189
	v_cmp_gt_u32_e32 vcc, 16, v208
	s_waitcnt vmcnt(0)
	v_fmamk_f32 v48, v190, 0x3fb8aa3b, v32
	v_add_u32_e32 v211, 1, v189
	v_cmp_gt_u32_e64 s[46:47], 16, v211
	v_cndmask_b32_e32 v48, v210, v48, vcc
	v_fmamk_f32 v49, v191, 0x3fb8aa3b, v33
	v_add_u32_e32 v208, 2, v189
	v_cmp_gt_u32_e32 vcc, 16, v208
	v_cndmask_b32_e64 v49, v210, v49, s[46:47]
	v_fmamk_f32 v50, v192, 0x3fb8aa3b, v34
	v_add_u32_e32 v211, 3, v189
	v_cmp_gt_u32_e64 s[46:47], 16, v211
	v_cndmask_b32_e32 v50, v210, v50, vcc
	v_fmamk_f32 v51, v193, 0x3fb8aa3b, v35
	v_add_u32_e32 v208, 8, v189
	v_cmp_gt_u32_e32 vcc, 16, v208
	v_cndmask_b32_e64 v51, v210, v51, s[46:47]
	v_fmamk_f32 v52, v194, 0x3fb8aa3b, v36
	v_add_u32_e32 v211, 9, v189
	v_cmp_gt_u32_e64 s[46:47], 16, v211
	v_cndmask_b32_e32 v52, v210, v52, vcc
	v_fmamk_f32 v53, v195, 0x3fb8aa3b, v37
	v_add_u32_e32 v208, 10, v189
	v_cmp_gt_u32_e32 vcc, 16, v208
	v_cndmask_b32_e64 v53, v210, v53, s[46:47]
	v_fmamk_f32 v54, v196, 0x3fb8aa3b, v38
	v_add_u32_e32 v211, 11, v189
	v_cmp_gt_u32_e64 s[46:47], 16, v211
	v_cndmask_b32_e32 v54, v210, v54, vcc
	v_fmamk_f32 v55, v197, 0x3fb8aa3b, v39
	v_add_u32_e32 v208, 16, v189
	v_cmp_gt_u32_e32 vcc, 16, v208
	v_cndmask_b32_e64 v55, v210, v55, s[46:47]
	v_fmamk_f32 v56, v198, 0x3fb8aa3b, v40
	v_add_u32_e32 v211, 17, v189
	v_cmp_gt_u32_e64 s[46:47], 16, v211
	v_cndmask_b32_e32 v56, v210, v56, vcc
	v_fmamk_f32 v57, v199, 0x3fb8aa3b, v41
	v_add_u32_e32 v208, 18, v189
	v_cmp_gt_u32_e32 vcc, 16, v208
	v_cndmask_b32_e64 v57, v210, v57, s[46:47]
	v_fmamk_f32 v58, v200, 0x3fb8aa3b, v42
	v_add_u32_e32 v211, 19, v189
	v_cmp_gt_u32_e64 s[46:47], 16, v211
	v_cndmask_b32_e32 v58, v210, v58, vcc
	v_fmamk_f32 v59, v201, 0x3fb8aa3b, v43
	v_add_u32_e32 v208, 24, v189
	v_cmp_gt_u32_e32 vcc, 16, v208
	v_cndmask_b32_e64 v59, v210, v59, s[46:47]
	v_fmamk_f32 v60, v202, 0x3fb8aa3b, v44
	v_add_u32_e32 v211, 25, v189
	v_cmp_gt_u32_e64 s[46:47], 16, v211
	v_cndmask_b32_e32 v60, v210, v60, vcc
	v_fmamk_f32 v61, v203, 0x3fb8aa3b, v45
	v_add_u32_e32 v208, 26, v189
	v_cmp_gt_u32_e32 vcc, 16, v208
	v_cndmask_b32_e64 v61, v210, v61, s[46:47]
	v_fmamk_f32 v62, v204, 0x3fb8aa3b, v46
	v_add_u32_e32 v211, 27, v189
	v_cmp_gt_u32_e64 s[46:47], 16, v211
	v_cndmask_b32_e32 v62, v210, v62, vcc
	v_fmamk_f32 v63, v205, 0x3fb8aa3b, v47
	s_nop 0
	v_cndmask_b32_e64 v63, v210, v63, s[46:47]
	s_mov_b64 s[8:9], exec
	s_branch .LBB0_391
